# GLU epilogue: packed f32 math (pk_fma with pre-scaled bias, pk_add, pk_mul) - 40 instead of 56 VALU per 8 outputs
# speedup vs baseline: 1.0018x; 1.0018x over previous
; __device__ __forceinline__ unsigned cvt_pk_bf16(float lo, float hi) { unsigned r; asm volatile("v_cvt_pk_bf16_f32 %0, %1, %2" : "=v"(r) : "v"(lo), "v"(hi)); return r; }
; __device__ __forceinline__ float sigm(float v) { return __builtin_amdgcn_rcpf(1.0f + __builtin_amdgcn_exp2f(-1.4426950408889634f * v)); }
;     __device__ __forceinline__ void operator()(const f32x4 (&acc)[2][2][4][2], const Unit& u, int wr, int wc, int fr, int fq) const {
;     ...
;         const int row0 = u.pm * BM + wr * 64 + fr, col0 = wc * 32 + 8 * fq;
; #pragma unroll
;         for (int bj = 0; bj < 2; ++bj)
; #pragma unroll
;             for (int n = 0; n < 2; ++n) {
;                 const int c = col0 + bj * HALF + 4 * n;
;                 const f32x4 bv = *(const f32x4*)(bias + c);
; #pragma unroll
;                 for (int ai = 0; ai < 2; ++ai)
; #pragma unroll
;                     for (int m = 0; m < 4; ++m) {
;                         const size_t row = (size_t)(row0 + ai * HALF + m * 16);
;                         const f32x4 v = acc[ai][bj][m][n] + bv;
;                         const u32x2 yv = *(const u32x2*)(YGS + row * 256 + c);
;                         const float y0 = __uint_as_float(yv.x << 16), y1 = __uint_as_float(yv.x & 0xffff0000u), y2 = __uint_as_float(yv.y << 16), y3 = __uint_as_float(yv.y & 0xffff0000u);
;                         u32x2 w; w.x = cvt_pk_bf16(y0 * sigm(v[0]), y1 * sigm(v[1])); w.y = cvt_pk_bf16(y2 * sigm(v[2]), y3 * sigm(v[3]));
;                         *(u32x2*)(MIX + row * 1024 + 256 + c) = w;
;                         if (m & 1) asm volatile("" ::: "memory");
;                     }
.LBB0_843:
	v_lshl_add_u32 v154, s54, 8, v156
	s_and_b64 vcc, exec, s[0:1]
	s_mov_b64 s[0:1], -1
	s_mov_b32 s98, 0xbfb8aa3b
	s_mov_b32 s99, 0xbfb8aa3b
	v_mov_b32_e32 v242, 1.0
	v_mov_b32_e32 v243, 1.0
	global_load_dwordx4 v[128:131], v[138:139], off
	global_load_dwordx4 v[208:211], v[138:139], off offset:16
	v_lshlrev_b32_e32 v220, 9, v154
	v_lshl_add_u64 v[148:149], v[140:141], 0, v[220:221]
	global_load_dwordx4 v[160:163], v[148:149], off
	v_or_b32_e32 v152, 16, v154
	v_lshlrev_b32_e32 v220, 9, v152
	v_lshl_add_u64 v[148:149], v[140:141], 0, v[220:221]
	global_load_dwordx4 v[164:167], v[148:149], off
	v_or_b32_e32 v152, 32, v154
	v_lshlrev_b32_e32 v220, 9, v152
	v_lshl_add_u64 v[148:149], v[140:141], 0, v[220:221]
	global_load_dwordx4 v[168:171], v[148:149], off
	v_or_b32_e32 v152, 48, v154
	v_lshlrev_b32_e32 v220, 9, v152
	v_lshl_add_u64 v[148:149], v[140:141], 0, v[220:221]
	global_load_dwordx4 v[172:175], v[148:149], off
	v_or_b32_e32 v152, 0x80, v154
	v_lshlrev_b32_e32 v220, 9, v152
	v_lshl_add_u64 v[148:149], v[140:141], 0, v[220:221]
	global_load_dwordx4 v[176:179], v[148:149], off
	v_or_b32_e32 v152, 0x90, v154
	v_lshlrev_b32_e32 v220, 9, v152
	v_lshl_add_u64 v[148:149], v[140:141], 0, v[220:221]
	global_load_dwordx4 v[180:183], v[148:149], off
	v_or_b32_e32 v152, 0xa0, v154
	v_lshlrev_b32_e32 v220, 9, v152
	v_lshl_add_u64 v[148:149], v[140:141], 0, v[220:221]
	global_load_dwordx4 v[184:187], v[148:149], off
	v_or_b32_e32 v152, 0xb0, v154
	v_lshlrev_b32_e32 v220, 9, v152
	v_lshl_add_u64 v[148:149], v[140:141], 0, v[220:221]
	global_load_dwordx4 v[188:191], v[148:149], off
	v_lshlrev_b32_e32 v220, 9, v154
	v_lshl_add_u64 v[148:149], v[140:141], 0, v[220:221]
	global_load_dwordx4 v[192:195], v[148:149], off offset:256
	v_or_b32_e32 v152, 16, v154
	v_lshlrev_b32_e32 v220, 9, v152
	v_lshl_add_u64 v[148:149], v[140:141], 0, v[220:221]
	global_load_dwordx4 v[196:199], v[148:149], off offset:256
	v_or_b32_e32 v152, 32, v154
	v_lshlrev_b32_e32 v220, 9, v152
	v_lshl_add_u64 v[148:149], v[140:141], 0, v[220:221]
	global_load_dwordx4 v[200:203], v[148:149], off offset:256
	v_or_b32_e32 v152, 48, v154
	v_lshlrev_b32_e32 v220, 9, v152
	v_lshl_add_u64 v[148:149], v[140:141], 0, v[220:221]
	global_load_dwordx4 v[204:207], v[148:149], off offset:256
	s_waitcnt vmcnt(11)
	v_pk_mul_f32 v[128:129], v[128:129], s[98:99]
	v_pk_mul_f32 v[130:131], v[130:131], s[98:99]
	v_pk_mul_f32 v[208:209], v[208:209], s[98:99]
	v_pk_mul_f32 v[210:211], v[210:211], s[98:99]
	v_pk_fma_f32 v[124:125], v[124:125], s[98:99], v[128:129]
	v_pk_fma_f32 v[126:127], v[126:127], s[98:99], v[130:131]
	v_pk_fma_f32 v[92:93], v[92:93], s[98:99], v[208:209]
	v_pk_fma_f32 v[94:95], v[94:95], s[98:99], v[210:211]
	v_exp_f32_e32 v124, v124
	v_exp_f32_e32 v125, v125
	v_exp_f32_e32 v126, v126
	v_exp_f32_e32 v127, v127
	v_exp_f32_e32 v92, v92
	v_exp_f32_e32 v93, v93
	v_exp_f32_e32 v94, v94
	v_exp_f32_e32 v95, v95
	v_pk_add_f32 v[124:125], v[124:125], v[242:243]
	v_pk_add_f32 v[126:127], v[126:127], v[242:243]
	v_pk_add_f32 v[92:93], v[92:93], v[242:243]
	v_pk_add_f32 v[94:95], v[94:95], v[242:243]
	v_rcp_f32_e32 v124, v124
	v_rcp_f32_e32 v125, v125
	v_rcp_f32_e32 v126, v126
	v_rcp_f32_e32 v127, v127
	v_rcp_f32_e32 v92, v92
	v_rcp_f32_e32 v93, v93
	v_rcp_f32_e32 v94, v94
	v_rcp_f32_e32 v95, v95
	v_lshlrev_b32_e32 v244, 16, v160
	v_and_b32_e32 v245, 0xffff0000, v160
	v_lshlrev_b32_e32 v246, 16, v161
	v_and_b32_e32 v247, 0xffff0000, v161
	v_pk_mul_f32 v[124:125], v[124:125], v[244:245]
	v_pk_mul_f32 v[126:127], v[126:127], v[246:247]
	v_lshlrev_b32_e32 v244, 16, v162
	v_and_b32_e32 v245, 0xffff0000, v162
	v_lshlrev_b32_e32 v246, 16, v163
	v_and_b32_e32 v247, 0xffff0000, v163
	v_pk_mul_f32 v[92:93], v[92:93], v[244:245]
	v_pk_mul_f32 v[94:95], v[94:95], v[246:247]
	v_cvt_pk_bf16_f32 v124, v124, v125
	v_cvt_pk_bf16_f32 v125, v126, v127
	v_cvt_pk_bf16_f32 v126, v92, v93
	v_cvt_pk_bf16_f32 v127, v94, v95
	v_lshlrev_b32_e32 v220, 11, v154
	v_lshl_add_u64 v[150:151], v[142:143], 0, v[220:221]
	global_store_dwordx4 v[150:151], v[124:127], off offset:512
	global_load_dwordx4 v[92:95], v[138:139], off offset:512
	s_waitcnt vmcnt(12)
	v_pk_fma_f32 v[120:121], v[120:121], s[98:99], v[128:129]
	v_pk_fma_f32 v[122:123], v[122:123], s[98:99], v[130:131]
	v_pk_fma_f32 v[88:89], v[88:89], s[98:99], v[208:209]
	v_pk_fma_f32 v[90:91], v[90:91], s[98:99], v[210:211]
	v_exp_f32_e32 v120, v120
	v_exp_f32_e32 v121, v121
	v_exp_f32_e32 v122, v122
	v_exp_f32_e32 v123, v123
	v_exp_f32_e32 v88, v88
	v_exp_f32_e32 v89, v89
	v_exp_f32_e32 v90, v90
	v_exp_f32_e32 v91, v91
	v_pk_add_f32 v[120:121], v[120:121], v[242:243]
	v_pk_add_f32 v[122:123], v[122:123], v[242:243]
	v_pk_add_f32 v[88:89], v[88:89], v[242:243]
	v_pk_add_f32 v[90:91], v[90:91], v[242:243]
	v_rcp_f32_e32 v120, v120
	v_rcp_f32_e32 v121, v121
	v_rcp_f32_e32 v122, v122
	v_rcp_f32_e32 v123, v123
	v_rcp_f32_e32 v88, v88
	v_rcp_f32_e32 v89, v89
	v_rcp_f32_e32 v90, v90
	v_rcp_f32_e32 v91, v91
	v_lshlrev_b32_e32 v244, 16, v164
	v_and_b32_e32 v245, 0xffff0000, v164
	v_lshlrev_b32_e32 v246, 16, v165
	v_and_b32_e32 v247, 0xffff0000, v165
	v_pk_mul_f32 v[120:121], v[120:121], v[244:245]
	v_pk_mul_f32 v[122:123], v[122:123], v[246:247]
	v_lshlrev_b32_e32 v244, 16, v166
	v_and_b32_e32 v245, 0xffff0000, v166
	v_lshlrev_b32_e32 v246, 16, v167
	v_and_b32_e32 v247, 0xffff0000, v167
	v_pk_mul_f32 v[88:89], v[88:89], v[244:245]
	v_pk_mul_f32 v[90:91], v[90:91], v[246:247]
	v_cvt_pk_bf16_f32 v120, v120, v121
	v_cvt_pk_bf16_f32 v121, v122, v123
	v_cvt_pk_bf16_f32 v122, v88, v89
	v_cvt_pk_bf16_f32 v123, v90, v91
	v_or_b32_e32 v152, 16, v154
	v_lshlrev_b32_e32 v220, 11, v152
	v_lshl_add_u64 v[150:151], v[142:143], 0, v[220:221]
	global_store_dwordx4 v[150:151], v[120:123], off offset:512
	global_load_dwordx4 v[88:91], v[138:139], off offset:528
	s_waitcnt vmcnt(13)
; __device__ __forceinline__ unsigned cvt_pk_bf16(float lo, float hi) { unsigned r; asm volatile("v_cvt_pk_bf16_f32 %0, %1, %2" : "=v"(r) : "v"(lo), "v"(hi)); return r; }
; __device__ __forceinline__ float sigm(float v) { return __builtin_amdgcn_rcpf(1.0f + __builtin_amdgcn_exp2f(-1.4426950408889634f * v)); }
;     __device__ __forceinline__ void operator()(const f32x4 (&acc)[2][2][4][2], const Unit& u, int wr, int wc, int fr, int fq) const {
;     ...
;         const int row0 = u.pm * BM + wr * 64 + fr, col0 = wc * 32 + 8 * fq;
; #pragma unroll
;         for (int bj = 0; bj < 2; ++bj)
; #pragma unroll
;             for (int n = 0; n < 2; ++n) {
;                 const int c = col0 + bj * HALF + 4 * n;
;                 const f32x4 bv = *(const f32x4*)(bias + c);
; #pragma unroll
;                 for (int ai = 0; ai < 2; ++ai)
; #pragma unroll
;                     for (int m = 0; m < 4; ++m) {
;                         const size_t row = (size_t)(row0 + ai * HALF + m * 16);
;                         const f32x4 v = acc[ai][bj][m][n] + bv;
;                         const u32x2 yv = *(const u32x2*)(YGS + row * 256 + c);
;                         const float y0 = __uint_as_float(yv.x << 16), y1 = __uint_as_float(yv.x & 0xffff0000u), y2 = __uint_as_float(yv.y << 16), y3 = __uint_as_float(yv.y & 0xffff0000u);
;                         u32x2 w; w.x = cvt_pk_bf16(y0 * sigm(v[0]), y1 * sigm(v[1])); w.y = cvt_pk_bf16(y2 * sigm(v[2]), y3 * sigm(v[3]));
;                         *(u32x2*)(MIX + row * 1024 + 256 + c) = w;
;                         if (m & 1) asm volatile("" ::: "memory");
;                     }
	v_pk_fma_f32 v[116:117], v[116:117], s[98:99], v[128:129]
	v_pk_fma_f32 v[118:119], v[118:119], s[98:99], v[130:131]
	v_pk_fma_f32 v[84:85], v[84:85], s[98:99], v[208:209]
	v_pk_fma_f32 v[86:87], v[86:87], s[98:99], v[210:211]
	v_exp_f32_e32 v116, v116
	v_exp_f32_e32 v117, v117
	v_exp_f32_e32 v118, v118
	v_exp_f32_e32 v119, v119
	v_exp_f32_e32 v84, v84
	v_exp_f32_e32 v85, v85
	v_exp_f32_e32 v86, v86
	v_exp_f32_e32 v87, v87
	v_pk_add_f32 v[116:117], v[116:117], v[242:243]
	v_pk_add_f32 v[118:119], v[118:119], v[242:243]
	v_pk_add_f32 v[84:85], v[84:85], v[242:243]
	v_pk_add_f32 v[86:87], v[86:87], v[242:243]
	v_rcp_f32_e32 v116, v116
	v_rcp_f32_e32 v117, v117
	v_rcp_f32_e32 v118, v118
	v_rcp_f32_e32 v119, v119
	v_rcp_f32_e32 v84, v84
	v_rcp_f32_e32 v85, v85
	v_rcp_f32_e32 v86, v86
	v_rcp_f32_e32 v87, v87
	v_lshlrev_b32_e32 v244, 16, v168
	v_and_b32_e32 v245, 0xffff0000, v168
	v_lshlrev_b32_e32 v246, 16, v169
	v_and_b32_e32 v247, 0xffff0000, v169
	v_pk_mul_f32 v[116:117], v[116:117], v[244:245]
	v_pk_mul_f32 v[118:119], v[118:119], v[246:247]
	v_lshlrev_b32_e32 v244, 16, v170
	v_and_b32_e32 v245, 0xffff0000, v170
	v_lshlrev_b32_e32 v246, 16, v171
	v_and_b32_e32 v247, 0xffff0000, v171
	v_pk_mul_f32 v[84:85], v[84:85], v[244:245]
	v_pk_mul_f32 v[86:87], v[86:87], v[246:247]
	v_cvt_pk_bf16_f32 v116, v116, v117
	v_cvt_pk_bf16_f32 v117, v118, v119
	v_cvt_pk_bf16_f32 v118, v84, v85
	v_cvt_pk_bf16_f32 v119, v86, v87
	v_or_b32_e32 v152, 32, v154
	v_lshlrev_b32_e32 v220, 11, v152
	v_lshl_add_u64 v[150:151], v[142:143], 0, v[220:221]
	global_store_dwordx4 v[150:151], v[116:119], off offset:512
	v_or_b32_e32 v152, 0x80, v154
	v_lshlrev_b32_e32 v220, 9, v152
	v_lshl_add_u64 v[148:149], v[140:141], 0, v[220:221]
	global_load_dwordx4 v[84:87], v[148:149], off offset:256
	s_waitcnt vmcnt(14)
	v_pk_fma_f32 v[112:113], v[112:113], s[98:99], v[128:129]
	v_pk_fma_f32 v[114:115], v[114:115], s[98:99], v[130:131]
	v_pk_fma_f32 v[80:81], v[80:81], s[98:99], v[208:209]
	v_pk_fma_f32 v[82:83], v[82:83], s[98:99], v[210:211]
	v_exp_f32_e32 v112, v112
	v_exp_f32_e32 v113, v113
	v_exp_f32_e32 v114, v114
	v_exp_f32_e32 v115, v115
	v_exp_f32_e32 v80, v80
	v_exp_f32_e32 v81, v81
	v_exp_f32_e32 v82, v82
	v_exp_f32_e32 v83, v83
	v_pk_add_f32 v[112:113], v[112:113], v[242:243]
	v_pk_add_f32 v[114:115], v[114:115], v[242:243]
	v_pk_add_f32 v[80:81], v[80:81], v[242:243]
	v_pk_add_f32 v[82:83], v[82:83], v[242:243]
	v_rcp_f32_e32 v112, v112
	v_rcp_f32_e32 v113, v113
	v_rcp_f32_e32 v114, v114
	v_rcp_f32_e32 v115, v115
	v_rcp_f32_e32 v80, v80
	v_rcp_f32_e32 v81, v81
	v_rcp_f32_e32 v82, v82
	v_rcp_f32_e32 v83, v83
	v_lshlrev_b32_e32 v244, 16, v172
	v_and_b32_e32 v245, 0xffff0000, v172
	v_lshlrev_b32_e32 v246, 16, v173
	v_and_b32_e32 v247, 0xffff0000, v173
	v_pk_mul_f32 v[112:113], v[112:113], v[244:245]
	v_pk_mul_f32 v[114:115], v[114:115], v[246:247]
	v_lshlrev_b32_e32 v244, 16, v174
	v_and_b32_e32 v245, 0xffff0000, v174
	v_lshlrev_b32_e32 v246, 16, v175
	v_and_b32_e32 v247, 0xffff0000, v175
	v_pk_mul_f32 v[80:81], v[80:81], v[244:245]
	v_pk_mul_f32 v[82:83], v[82:83], v[246:247]
	v_cvt_pk_bf16_f32 v112, v112, v113
	v_cvt_pk_bf16_f32 v113, v114, v115
	v_cvt_pk_bf16_f32 v114, v80, v81
	v_cvt_pk_bf16_f32 v115, v82, v83
	v_or_b32_e32 v152, 48, v154
	v_lshlrev_b32_e32 v220, 11, v152
	v_lshl_add_u64 v[150:151], v[142:143], 0, v[220:221]
	global_store_dwordx4 v[150:151], v[112:115], off offset:512
	v_or_b32_e32 v152, 0x90, v154
	v_lshlrev_b32_e32 v220, 9, v152
	v_lshl_add_u64 v[148:149], v[140:141], 0, v[220:221]
	global_load_dwordx4 v[80:83], v[148:149], off offset:256
	s_waitcnt vmcnt(15)
	v_pk_fma_f32 v[108:109], v[108:109], s[98:99], v[128:129]
	v_pk_fma_f32 v[110:111], v[110:111], s[98:99], v[130:131]
	v_pk_fma_f32 v[76:77], v[76:77], s[98:99], v[208:209]
	v_pk_fma_f32 v[78:79], v[78:79], s[98:99], v[210:211]
	v_exp_f32_e32 v108, v108
	v_exp_f32_e32 v109, v109
	v_exp_f32_e32 v110, v110
	v_exp_f32_e32 v111, v111
	v_exp_f32_e32 v76, v76
	v_exp_f32_e32 v77, v77
	v_exp_f32_e32 v78, v78
	v_exp_f32_e32 v79, v79
	v_pk_add_f32 v[108:109], v[108:109], v[242:243]
	v_pk_add_f32 v[110:111], v[110:111], v[242:243]
	v_pk_add_f32 v[76:77], v[76:77], v[242:243]
	v_pk_add_f32 v[78:79], v[78:79], v[242:243]
	v_rcp_f32_e32 v108, v108
	v_rcp_f32_e32 v109, v109
	v_rcp_f32_e32 v110, v110
	v_rcp_f32_e32 v111, v111
	v_rcp_f32_e32 v76, v76
	v_rcp_f32_e32 v77, v77
	v_rcp_f32_e32 v78, v78
	v_rcp_f32_e32 v79, v79
	v_lshlrev_b32_e32 v244, 16, v176
	v_and_b32_e32 v245, 0xffff0000, v176
	v_lshlrev_b32_e32 v246, 16, v177
	v_and_b32_e32 v247, 0xffff0000, v177
	v_pk_mul_f32 v[108:109], v[108:109], v[244:245]
	v_pk_mul_f32 v[110:111], v[110:111], v[246:247]
	v_lshlrev_b32_e32 v244, 16, v178
	v_and_b32_e32 v245, 0xffff0000, v178
	v_lshlrev_b32_e32 v246, 16, v179
	v_and_b32_e32 v247, 0xffff0000, v179
	v_pk_mul_f32 v[76:77], v[76:77], v[244:245]
	v_pk_mul_f32 v[78:79], v[78:79], v[246:247]
	v_cvt_pk_bf16_f32 v108, v108, v109
	v_cvt_pk_bf16_f32 v109, v110, v111
	v_cvt_pk_bf16_f32 v110, v76, v77
	v_cvt_pk_bf16_f32 v111, v78, v79
	v_or_b32_e32 v152, 0x80, v154
	v_lshlrev_b32_e32 v220, 11, v152
	v_lshl_add_u64 v[150:151], v[142:143], 0, v[220:221]
	global_store_dwordx4 v[150:151], v[108:111], off offset:512
	v_or_b32_e32 v152, 0xa0, v154
	v_lshlrev_b32_e32 v220, 9, v152
	v_lshl_add_u64 v[148:149], v[140:141], 0, v[220:221]
	global_load_dwordx4 v[76:79], v[148:149], off offset:256
	s_waitcnt vmcnt(16)
; __device__ __forceinline__ unsigned cvt_pk_bf16(float lo, float hi) { unsigned r; asm volatile("v_cvt_pk_bf16_f32 %0, %1, %2" : "=v"(r) : "v"(lo), "v"(hi)); return r; }
; __device__ __forceinline__ float sigm(float v) { return __builtin_amdgcn_rcpf(1.0f + __builtin_amdgcn_exp2f(-1.4426950408889634f * v)); }
;     __device__ __forceinline__ void operator()(const f32x4 (&acc)[2][2][4][2], const Unit& u, int wr, int wc, int fr, int fq) const {
;     ...
;         const int row0 = u.pm * BM + wr * 64 + fr, col0 = wc * 32 + 8 * fq;
; #pragma unroll
;         for (int bj = 0; bj < 2; ++bj)
; #pragma unroll
;             for (int n = 0; n < 2; ++n) {
;                 const int c = col0 + bj * HALF + 4 * n;
;                 const f32x4 bv = *(const f32x4*)(bias + c);
; #pragma unroll
;                 for (int ai = 0; ai < 2; ++ai)
; #pragma unroll
;                     for (int m = 0; m < 4; ++m) {
;                         const size_t row = (size_t)(row0 + ai * HALF + m * 16);
;                         const f32x4 v = acc[ai][bj][m][n] + bv;
;                         const u32x2 yv = *(const u32x2*)(YGS + row * 256 + c);
;                         const float y0 = __uint_as_float(yv.x << 16), y1 = __uint_as_float(yv.x & 0xffff0000u), y2 = __uint_as_float(yv.y << 16), y3 = __uint_as_float(yv.y & 0xffff0000u);
;                         u32x2 w; w.x = cvt_pk_bf16(y0 * sigm(v[0]), y1 * sigm(v[1])); w.y = cvt_pk_bf16(y2 * sigm(v[2]), y3 * sigm(v[3]));
;                         *(u32x2*)(MIX + row * 1024 + 256 + c) = w;
;                         if (m & 1) asm volatile("" ::: "memory");
;                     }
	v_pk_fma_f32 v[104:105], v[104:105], s[98:99], v[128:129]
	v_pk_fma_f32 v[106:107], v[106:107], s[98:99], v[130:131]
	v_pk_fma_f32 v[72:73], v[72:73], s[98:99], v[208:209]
	v_pk_fma_f32 v[74:75], v[74:75], s[98:99], v[210:211]
	v_exp_f32_e32 v104, v104
	v_exp_f32_e32 v105, v105
	v_exp_f32_e32 v106, v106
	v_exp_f32_e32 v107, v107
	v_exp_f32_e32 v72, v72
	v_exp_f32_e32 v73, v73
	v_exp_f32_e32 v74, v74
	v_exp_f32_e32 v75, v75
	v_pk_add_f32 v[104:105], v[104:105], v[242:243]
	v_pk_add_f32 v[106:107], v[106:107], v[242:243]
	v_pk_add_f32 v[72:73], v[72:73], v[242:243]
	v_pk_add_f32 v[74:75], v[74:75], v[242:243]
	v_rcp_f32_e32 v104, v104
	v_rcp_f32_e32 v105, v105
	v_rcp_f32_e32 v106, v106
	v_rcp_f32_e32 v107, v107
	v_rcp_f32_e32 v72, v72
	v_rcp_f32_e32 v73, v73
	v_rcp_f32_e32 v74, v74
	v_rcp_f32_e32 v75, v75
	v_lshlrev_b32_e32 v244, 16, v180
	v_and_b32_e32 v245, 0xffff0000, v180
	v_lshlrev_b32_e32 v246, 16, v181
	v_and_b32_e32 v247, 0xffff0000, v181
	v_pk_mul_f32 v[104:105], v[104:105], v[244:245]
	v_pk_mul_f32 v[106:107], v[106:107], v[246:247]
	v_lshlrev_b32_e32 v244, 16, v182
	v_and_b32_e32 v245, 0xffff0000, v182
	v_lshlrev_b32_e32 v246, 16, v183
	v_and_b32_e32 v247, 0xffff0000, v183
	v_pk_mul_f32 v[72:73], v[72:73], v[244:245]
	v_pk_mul_f32 v[74:75], v[74:75], v[246:247]
	v_cvt_pk_bf16_f32 v104, v104, v105
	v_cvt_pk_bf16_f32 v105, v106, v107
	v_cvt_pk_bf16_f32 v106, v72, v73
	v_cvt_pk_bf16_f32 v107, v74, v75
	v_or_b32_e32 v152, 0x90, v154
	v_lshlrev_b32_e32 v220, 11, v152
	v_lshl_add_u64 v[150:151], v[142:143], 0, v[220:221]
	global_store_dwordx4 v[150:151], v[104:107], off offset:512
	v_or_b32_e32 v152, 0xb0, v154
	v_lshlrev_b32_e32 v220, 9, v152
	v_lshl_add_u64 v[148:149], v[140:141], 0, v[220:221]
	global_load_dwordx4 v[72:75], v[148:149], off offset:256
	s_waitcnt vmcnt(17)
	v_pk_fma_f32 v[100:101], v[100:101], s[98:99], v[128:129]
	v_pk_fma_f32 v[102:103], v[102:103], s[98:99], v[130:131]
	v_pk_fma_f32 v[68:69], v[68:69], s[98:99], v[208:209]
	v_pk_fma_f32 v[70:71], v[70:71], s[98:99], v[210:211]
	v_exp_f32_e32 v100, v100
	v_exp_f32_e32 v101, v101
	v_exp_f32_e32 v102, v102
	v_exp_f32_e32 v103, v103
	v_exp_f32_e32 v68, v68
	v_exp_f32_e32 v69, v69
	v_exp_f32_e32 v70, v70
	v_exp_f32_e32 v71, v71
	v_pk_add_f32 v[100:101], v[100:101], v[242:243]
	v_pk_add_f32 v[102:103], v[102:103], v[242:243]
	v_pk_add_f32 v[68:69], v[68:69], v[242:243]
	v_pk_add_f32 v[70:71], v[70:71], v[242:243]
	v_rcp_f32_e32 v100, v100
	v_rcp_f32_e32 v101, v101
	v_rcp_f32_e32 v102, v102
	v_rcp_f32_e32 v103, v103
	v_rcp_f32_e32 v68, v68
	v_rcp_f32_e32 v69, v69
	v_rcp_f32_e32 v70, v70
	v_rcp_f32_e32 v71, v71
	v_lshlrev_b32_e32 v244, 16, v184
	v_and_b32_e32 v245, 0xffff0000, v184
	v_lshlrev_b32_e32 v246, 16, v185
	v_and_b32_e32 v247, 0xffff0000, v185
	v_pk_mul_f32 v[100:101], v[100:101], v[244:245]
	v_pk_mul_f32 v[102:103], v[102:103], v[246:247]
	v_lshlrev_b32_e32 v244, 16, v186
	v_and_b32_e32 v245, 0xffff0000, v186
	v_lshlrev_b32_e32 v246, 16, v187
	v_and_b32_e32 v247, 0xffff0000, v187
	v_pk_mul_f32 v[68:69], v[68:69], v[244:245]
	v_pk_mul_f32 v[70:71], v[70:71], v[246:247]
	v_cvt_pk_bf16_f32 v100, v100, v101
	v_cvt_pk_bf16_f32 v101, v102, v103
	v_cvt_pk_bf16_f32 v102, v68, v69
	v_cvt_pk_bf16_f32 v103, v70, v71
	v_or_b32_e32 v152, 0xa0, v154
	v_lshlrev_b32_e32 v220, 11, v152
	v_lshl_add_u64 v[150:151], v[142:143], 0, v[220:221]
	global_store_dwordx4 v[150:151], v[100:103], off offset:512
	s_waitcnt vmcnt(17)
	v_pk_fma_f32 v[96:97], v[96:97], s[98:99], v[128:129]
	v_pk_fma_f32 v[98:99], v[98:99], s[98:99], v[130:131]
	v_pk_fma_f32 v[64:65], v[64:65], s[98:99], v[208:209]
	v_pk_fma_f32 v[66:67], v[66:67], s[98:99], v[210:211]
	v_exp_f32_e32 v96, v96
	v_exp_f32_e32 v97, v97
	v_exp_f32_e32 v98, v98
	v_exp_f32_e32 v99, v99
	v_exp_f32_e32 v64, v64
	v_exp_f32_e32 v65, v65
	v_exp_f32_e32 v66, v66
	v_exp_f32_e32 v67, v67
	v_pk_add_f32 v[96:97], v[96:97], v[242:243]
	v_pk_add_f32 v[98:99], v[98:99], v[242:243]
	v_pk_add_f32 v[64:65], v[64:65], v[242:243]
	v_pk_add_f32 v[66:67], v[66:67], v[242:243]
	v_rcp_f32_e32 v96, v96
	v_rcp_f32_e32 v97, v97
	v_rcp_f32_e32 v98, v98
	v_rcp_f32_e32 v99, v99
	v_rcp_f32_e32 v64, v64
	v_rcp_f32_e32 v65, v65
	v_rcp_f32_e32 v66, v66
	v_rcp_f32_e32 v67, v67
	v_lshlrev_b32_e32 v244, 16, v188
	v_and_b32_e32 v245, 0xffff0000, v188
	v_lshlrev_b32_e32 v246, 16, v189
	v_and_b32_e32 v247, 0xffff0000, v189
	v_pk_mul_f32 v[96:97], v[96:97], v[244:245]
	v_pk_mul_f32 v[98:99], v[98:99], v[246:247]
	v_lshlrev_b32_e32 v244, 16, v190
	v_and_b32_e32 v245, 0xffff0000, v190
	v_lshlrev_b32_e32 v246, 16, v191
	v_and_b32_e32 v247, 0xffff0000, v191
	v_pk_mul_f32 v[64:65], v[64:65], v[244:245]
	v_pk_mul_f32 v[66:67], v[66:67], v[246:247]
	v_cvt_pk_bf16_f32 v96, v96, v97
	v_cvt_pk_bf16_f32 v97, v98, v99
	v_cvt_pk_bf16_f32 v98, v64, v65
	v_cvt_pk_bf16_f32 v99, v66, v67
	v_or_b32_e32 v152, 0xb0, v154
	v_lshlrev_b32_e32 v220, 11, v152
	v_lshl_add_u64 v[150:151], v[142:143], 0, v[220:221]
	global_store_dwordx4 v[150:151], v[96:99], off offset:512
	s_waitcnt vmcnt(10)
; __device__ __forceinline__ unsigned cvt_pk_bf16(float lo, float hi) { unsigned r; asm volatile("v_cvt_pk_bf16_f32 %0, %1, %2" : "=v"(r) : "v"(lo), "v"(hi)); return r; }
; __device__ __forceinline__ float sigm(float v) { return __builtin_amdgcn_rcpf(1.0f + __builtin_amdgcn_exp2f(-1.4426950408889634f * v)); }
;     __device__ __forceinline__ void operator()(const f32x4 (&acc)[2][2][4][2], const Unit& u, int wr, int wc, int fr, int fq) const {
;     ...
;         const int row0 = u.pm * BM + wr * 64 + fr, col0 = wc * 32 + 8 * fq;
; #pragma unroll
;         for (int bj = 0; bj < 2; ++bj)
; #pragma unroll
;             for (int n = 0; n < 2; ++n) {
;                 const int c = col0 + bj * HALF + 4 * n;
;                 const f32x4 bv = *(const f32x4*)(bias + c);
; #pragma unroll
;                 for (int ai = 0; ai < 2; ++ai)
; #pragma unroll
;                     for (int m = 0; m < 4; ++m) {
;                         const size_t row = (size_t)(row0 + ai * HALF + m * 16);
;                         const f32x4 v = acc[ai][bj][m][n] + bv;
;                         const u32x2 yv = *(const u32x2*)(YGS + row * 256 + c);
;                         const float y0 = __uint_as_float(yv.x << 16), y1 = __uint_as_float(yv.x & 0xffff0000u), y2 = __uint_as_float(yv.y << 16), y3 = __uint_as_float(yv.y & 0xffff0000u);
;                         u32x2 w; w.x = cvt_pk_bf16(y0 * sigm(v[0]), y1 * sigm(v[1])); w.y = cvt_pk_bf16(y2 * sigm(v[2]), y3 * sigm(v[3]));
;                         *(u32x2*)(MIX + row * 1024 + 256 + c) = w;
;                         if (m & 1) asm volatile("" ::: "memory");
;                     }
	v_pk_mul_f32 v[92:93], v[92:93], s[98:99]
	v_pk_mul_f32 v[94:95], v[94:95], s[98:99]
	v_pk_mul_f32 v[88:89], v[88:89], s[98:99]
	v_pk_mul_f32 v[90:91], v[90:91], s[98:99]
	v_pk_fma_f32 v[60:61], v[60:61], s[98:99], v[92:93]
	v_pk_fma_f32 v[62:63], v[62:63], s[98:99], v[94:95]
	v_pk_fma_f32 v[28:29], v[28:29], s[98:99], v[88:89]
	v_pk_fma_f32 v[30:31], v[30:31], s[98:99], v[90:91]
	v_exp_f32_e32 v60, v60
	v_exp_f32_e32 v61, v61
	v_exp_f32_e32 v62, v62
	v_exp_f32_e32 v63, v63
	v_exp_f32_e32 v28, v28
	v_exp_f32_e32 v29, v29
	v_exp_f32_e32 v30, v30
	v_exp_f32_e32 v31, v31
	v_pk_add_f32 v[60:61], v[60:61], v[242:243]
	v_pk_add_f32 v[62:63], v[62:63], v[242:243]
	v_pk_add_f32 v[28:29], v[28:29], v[242:243]
	v_pk_add_f32 v[30:31], v[30:31], v[242:243]
	v_rcp_f32_e32 v60, v60
	v_rcp_f32_e32 v61, v61
	v_rcp_f32_e32 v62, v62
	v_rcp_f32_e32 v63, v63
	v_rcp_f32_e32 v28, v28
	v_rcp_f32_e32 v29, v29
	v_rcp_f32_e32 v30, v30
	v_rcp_f32_e32 v31, v31
	v_lshlrev_b32_e32 v244, 16, v192
	v_and_b32_e32 v245, 0xffff0000, v192
	v_lshlrev_b32_e32 v246, 16, v193
	v_and_b32_e32 v247, 0xffff0000, v193
	v_pk_mul_f32 v[60:61], v[60:61], v[244:245]
	v_pk_mul_f32 v[62:63], v[62:63], v[246:247]
	v_lshlrev_b32_e32 v244, 16, v194
	v_and_b32_e32 v245, 0xffff0000, v194
	v_lshlrev_b32_e32 v246, 16, v195
	v_and_b32_e32 v247, 0xffff0000, v195
	v_pk_mul_f32 v[28:29], v[28:29], v[244:245]
	v_pk_mul_f32 v[30:31], v[30:31], v[246:247]
	v_cvt_pk_bf16_f32 v60, v60, v61
	v_cvt_pk_bf16_f32 v61, v62, v63
	v_cvt_pk_bf16_f32 v62, v28, v29
	v_cvt_pk_bf16_f32 v63, v30, v31
	v_lshlrev_b32_e32 v220, 11, v154
	v_lshl_add_u64 v[150:151], v[142:143], 0, v[220:221]
	global_store_dwordx4 v[150:151], v[60:63], off offset:768
	v_pk_fma_f32 v[56:57], v[56:57], s[98:99], v[92:93]
	v_pk_fma_f32 v[58:59], v[58:59], s[98:99], v[94:95]
	v_pk_fma_f32 v[24:25], v[24:25], s[98:99], v[88:89]
	v_pk_fma_f32 v[26:27], v[26:27], s[98:99], v[90:91]
	v_exp_f32_e32 v56, v56
	v_exp_f32_e32 v57, v57
	v_exp_f32_e32 v58, v58
	v_exp_f32_e32 v59, v59
	v_exp_f32_e32 v24, v24
	v_exp_f32_e32 v25, v25
	v_exp_f32_e32 v26, v26
	v_exp_f32_e32 v27, v27
	v_pk_add_f32 v[56:57], v[56:57], v[242:243]
	v_pk_add_f32 v[58:59], v[58:59], v[242:243]
	v_pk_add_f32 v[24:25], v[24:25], v[242:243]
	v_pk_add_f32 v[26:27], v[26:27], v[242:243]
	v_rcp_f32_e32 v56, v56
	v_rcp_f32_e32 v57, v57
	v_rcp_f32_e32 v58, v58
	v_rcp_f32_e32 v59, v59
	v_rcp_f32_e32 v24, v24
	v_rcp_f32_e32 v25, v25
	v_rcp_f32_e32 v26, v26
	v_rcp_f32_e32 v27, v27
	v_lshlrev_b32_e32 v244, 16, v196
	v_and_b32_e32 v245, 0xffff0000, v196
	v_lshlrev_b32_e32 v246, 16, v197
	v_and_b32_e32 v247, 0xffff0000, v197
	v_pk_mul_f32 v[56:57], v[56:57], v[244:245]
	v_pk_mul_f32 v[58:59], v[58:59], v[246:247]
	v_lshlrev_b32_e32 v244, 16, v198
	v_and_b32_e32 v245, 0xffff0000, v198
	v_lshlrev_b32_e32 v246, 16, v199
	v_and_b32_e32 v247, 0xffff0000, v199
	v_pk_mul_f32 v[24:25], v[24:25], v[244:245]
	v_pk_mul_f32 v[26:27], v[26:27], v[246:247]
	v_cvt_pk_bf16_f32 v56, v56, v57
	v_cvt_pk_bf16_f32 v57, v58, v59
	v_cvt_pk_bf16_f32 v58, v24, v25
	v_cvt_pk_bf16_f32 v59, v26, v27
	v_or_b32_e32 v152, 16, v154
	v_lshlrev_b32_e32 v220, 11, v152
	v_lshl_add_u64 v[150:151], v[142:143], 0, v[220:221]
	global_store_dwordx4 v[150:151], v[56:59], off offset:768
	v_pk_fma_f32 v[52:53], v[52:53], s[98:99], v[92:93]
	v_pk_fma_f32 v[54:55], v[54:55], s[98:99], v[94:95]
	v_pk_fma_f32 v[20:21], v[20:21], s[98:99], v[88:89]
	v_pk_fma_f32 v[22:23], v[22:23], s[98:99], v[90:91]
	v_exp_f32_e32 v52, v52
	v_exp_f32_e32 v53, v53
	v_exp_f32_e32 v54, v54
	v_exp_f32_e32 v55, v55
	v_exp_f32_e32 v20, v20
	v_exp_f32_e32 v21, v21
	v_exp_f32_e32 v22, v22
	v_exp_f32_e32 v23, v23
	v_pk_add_f32 v[52:53], v[52:53], v[242:243]
	v_pk_add_f32 v[54:55], v[54:55], v[242:243]
	v_pk_add_f32 v[20:21], v[20:21], v[242:243]
	v_pk_add_f32 v[22:23], v[22:23], v[242:243]
	v_rcp_f32_e32 v52, v52
	v_rcp_f32_e32 v53, v53
	v_rcp_f32_e32 v54, v54
	v_rcp_f32_e32 v55, v55
	v_rcp_f32_e32 v20, v20
	v_rcp_f32_e32 v21, v21
	v_rcp_f32_e32 v22, v22
	v_rcp_f32_e32 v23, v23
	v_lshlrev_b32_e32 v244, 16, v200
	v_and_b32_e32 v245, 0xffff0000, v200
	v_lshlrev_b32_e32 v246, 16, v201
	v_and_b32_e32 v247, 0xffff0000, v201
	v_pk_mul_f32 v[52:53], v[52:53], v[244:245]
	v_pk_mul_f32 v[54:55], v[54:55], v[246:247]
	v_lshlrev_b32_e32 v244, 16, v202
	v_and_b32_e32 v245, 0xffff0000, v202
	v_lshlrev_b32_e32 v246, 16, v203
	v_and_b32_e32 v247, 0xffff0000, v203
	v_pk_mul_f32 v[20:21], v[20:21], v[244:245]
	v_pk_mul_f32 v[22:23], v[22:23], v[246:247]
	v_cvt_pk_bf16_f32 v52, v52, v53
	v_cvt_pk_bf16_f32 v53, v54, v55
	v_cvt_pk_bf16_f32 v54, v20, v21
	v_cvt_pk_bf16_f32 v55, v22, v23
	v_or_b32_e32 v152, 32, v154
	v_lshlrev_b32_e32 v220, 11, v152
	v_lshl_add_u64 v[150:151], v[142:143], 0, v[220:221]
	global_store_dwordx4 v[150:151], v[52:55], off offset:768
	v_pk_fma_f32 v[48:49], v[48:49], s[98:99], v[92:93]
	v_pk_fma_f32 v[50:51], v[50:51], s[98:99], v[94:95]
	v_pk_fma_f32 v[16:17], v[16:17], s[98:99], v[88:89]
	v_pk_fma_f32 v[18:19], v[18:19], s[98:99], v[90:91]
	v_exp_f32_e32 v48, v48
	v_exp_f32_e32 v49, v49
	v_exp_f32_e32 v50, v50
	v_exp_f32_e32 v51, v51
	v_exp_f32_e32 v16, v16
	v_exp_f32_e32 v17, v17
	v_exp_f32_e32 v18, v18
	v_exp_f32_e32 v19, v19
	v_pk_add_f32 v[48:49], v[48:49], v[242:243]
	v_pk_add_f32 v[50:51], v[50:51], v[242:243]
	v_pk_add_f32 v[16:17], v[16:17], v[242:243]
	v_pk_add_f32 v[18:19], v[18:19], v[242:243]
	v_rcp_f32_e32 v48, v48
	v_rcp_f32_e32 v49, v49
	v_rcp_f32_e32 v50, v50
	v_rcp_f32_e32 v51, v51
	v_rcp_f32_e32 v16, v16
	v_rcp_f32_e32 v17, v17
	v_rcp_f32_e32 v18, v18
	v_rcp_f32_e32 v19, v19
	v_lshlrev_b32_e32 v244, 16, v204
	v_and_b32_e32 v245, 0xffff0000, v204
	v_lshlrev_b32_e32 v246, 16, v205
	v_and_b32_e32 v247, 0xffff0000, v205
	v_pk_mul_f32 v[48:49], v[48:49], v[244:245]
	v_pk_mul_f32 v[50:51], v[50:51], v[246:247]
	v_lshlrev_b32_e32 v244, 16, v206
	v_and_b32_e32 v245, 0xffff0000, v206
	v_lshlrev_b32_e32 v246, 16, v207
	v_and_b32_e32 v247, 0xffff0000, v207
	v_pk_mul_f32 v[16:17], v[16:17], v[244:245]
	v_pk_mul_f32 v[18:19], v[18:19], v[246:247]
	v_cvt_pk_bf16_f32 v48, v48, v49
	v_cvt_pk_bf16_f32 v49, v50, v51
	v_cvt_pk_bf16_f32 v50, v16, v17
	v_cvt_pk_bf16_f32 v51, v18, v19
	v_or_b32_e32 v152, 48, v154
	v_lshlrev_b32_e32 v220, 11, v152
	v_lshl_add_u64 v[150:151], v[142:143], 0, v[220:221]
	global_store_dwordx4 v[150:151], v[48:51], off offset:768
	s_waitcnt vmcnt(12)
; __device__ __forceinline__ unsigned cvt_pk_bf16(float lo, float hi) { unsigned r; asm volatile("v_cvt_pk_bf16_f32 %0, %1, %2" : "=v"(r) : "v"(lo), "v"(hi)); return r; }
; __device__ __forceinline__ float sigm(float v) { return __builtin_amdgcn_rcpf(1.0f + __builtin_amdgcn_exp2f(-1.4426950408889634f * v)); }
;     __device__ __forceinline__ void operator()(const f32x4 (&acc)[2][2][4][2], const Unit& u, int wr, int wc, int fr, int fq) const {
;     ...
;         const int row0 = u.pm * BM + wr * 64 + fr, col0 = wc * 32 + 8 * fq;
; #pragma unroll
;         for (int bj = 0; bj < 2; ++bj)
; #pragma unroll
;             for (int n = 0; n < 2; ++n) {
;                 const int c = col0 + bj * HALF + 4 * n;
;                 const f32x4 bv = *(const f32x4*)(bias + c);
; #pragma unroll
;                 for (int ai = 0; ai < 2; ++ai)
; #pragma unroll
;                     for (int m = 0; m < 4; ++m) {
;                         const size_t row = (size_t)(row0 + ai * HALF + m * 16);
;                         const f32x4 v = acc[ai][bj][m][n] + bv;
;                         const u32x2 yv = *(const u32x2*)(YGS + row * 256 + c);
;                         const float y0 = __uint_as_float(yv.x << 16), y1 = __uint_as_float(yv.x & 0xffff0000u), y2 = __uint_as_float(yv.y << 16), y3 = __uint_as_float(yv.y & 0xffff0000u);
;                         u32x2 w; w.x = cvt_pk_bf16(y0 * sigm(v[0]), y1 * sigm(v[1])); w.y = cvt_pk_bf16(y2 * sigm(v[2]), y3 * sigm(v[3]));
;                         *(u32x2*)(MIX + row * 1024 + 256 + c) = w;
;                         if (m & 1) asm volatile("" ::: "memory");
;                     }
	v_pk_fma_f32 v[44:45], v[44:45], s[98:99], v[92:93]
	v_pk_fma_f32 v[46:47], v[46:47], s[98:99], v[94:95]
	v_pk_fma_f32 v[12:13], v[12:13], s[98:99], v[88:89]
	v_pk_fma_f32 v[14:15], v[14:15], s[98:99], v[90:91]
	v_exp_f32_e32 v44, v44
	v_exp_f32_e32 v45, v45
	v_exp_f32_e32 v46, v46
	v_exp_f32_e32 v47, v47
	v_exp_f32_e32 v12, v12
	v_exp_f32_e32 v13, v13
	v_exp_f32_e32 v14, v14
	v_exp_f32_e32 v15, v15
	v_pk_add_f32 v[44:45], v[44:45], v[242:243]
	v_pk_add_f32 v[46:47], v[46:47], v[242:243]
	v_pk_add_f32 v[12:13], v[12:13], v[242:243]
	v_pk_add_f32 v[14:15], v[14:15], v[242:243]
	v_rcp_f32_e32 v44, v44
	v_rcp_f32_e32 v45, v45
	v_rcp_f32_e32 v46, v46
	v_rcp_f32_e32 v47, v47
	v_rcp_f32_e32 v12, v12
	v_rcp_f32_e32 v13, v13
	v_rcp_f32_e32 v14, v14
	v_rcp_f32_e32 v15, v15
	v_lshlrev_b32_e32 v244, 16, v84
	v_and_b32_e32 v245, 0xffff0000, v84
	v_lshlrev_b32_e32 v246, 16, v85
	v_and_b32_e32 v247, 0xffff0000, v85
	v_pk_mul_f32 v[44:45], v[44:45], v[244:245]
	v_pk_mul_f32 v[46:47], v[46:47], v[246:247]
	v_lshlrev_b32_e32 v244, 16, v86
	v_and_b32_e32 v245, 0xffff0000, v86
	v_lshlrev_b32_e32 v246, 16, v87
	v_and_b32_e32 v247, 0xffff0000, v87
	v_pk_mul_f32 v[12:13], v[12:13], v[244:245]
	v_pk_mul_f32 v[14:15], v[14:15], v[246:247]
	v_cvt_pk_bf16_f32 v44, v44, v45
	v_cvt_pk_bf16_f32 v45, v46, v47
	v_cvt_pk_bf16_f32 v46, v12, v13
	v_cvt_pk_bf16_f32 v47, v14, v15
	v_or_b32_e32 v152, 0x80, v154
	v_lshlrev_b32_e32 v220, 11, v152
	v_lshl_add_u64 v[150:151], v[142:143], 0, v[220:221]
	global_store_dwordx4 v[150:151], v[44:47], off offset:768
	s_waitcnt vmcnt(11)
	v_pk_fma_f32 v[40:41], v[40:41], s[98:99], v[92:93]
	v_pk_fma_f32 v[42:43], v[42:43], s[98:99], v[94:95]
	v_pk_fma_f32 v[8:9], v[8:9], s[98:99], v[88:89]
	v_pk_fma_f32 v[10:11], v[10:11], s[98:99], v[90:91]
	v_exp_f32_e32 v40, v40
	v_exp_f32_e32 v41, v41
	v_exp_f32_e32 v42, v42
	v_exp_f32_e32 v43, v43
	v_exp_f32_e32 v8, v8
	v_exp_f32_e32 v9, v9
	v_exp_f32_e32 v10, v10
	v_exp_f32_e32 v11, v11
	v_pk_add_f32 v[40:41], v[40:41], v[242:243]
	v_pk_add_f32 v[42:43], v[42:43], v[242:243]
	v_pk_add_f32 v[8:9], v[8:9], v[242:243]
	v_pk_add_f32 v[10:11], v[10:11], v[242:243]
	v_rcp_f32_e32 v40, v40
	v_rcp_f32_e32 v41, v41
	v_rcp_f32_e32 v42, v42
	v_rcp_f32_e32 v43, v43
	v_rcp_f32_e32 v8, v8
	v_rcp_f32_e32 v9, v9
	v_rcp_f32_e32 v10, v10
	v_rcp_f32_e32 v11, v11
	v_lshlrev_b32_e32 v244, 16, v80
	v_and_b32_e32 v245, 0xffff0000, v80
	v_lshlrev_b32_e32 v246, 16, v81
	v_and_b32_e32 v247, 0xffff0000, v81
	v_pk_mul_f32 v[40:41], v[40:41], v[244:245]
	v_pk_mul_f32 v[42:43], v[42:43], v[246:247]
	v_lshlrev_b32_e32 v244, 16, v82
	v_and_b32_e32 v245, 0xffff0000, v82
	v_lshlrev_b32_e32 v246, 16, v83
	v_and_b32_e32 v247, 0xffff0000, v83
	v_pk_mul_f32 v[8:9], v[8:9], v[244:245]
	v_pk_mul_f32 v[10:11], v[10:11], v[246:247]
	v_cvt_pk_bf16_f32 v40, v40, v41
	v_cvt_pk_bf16_f32 v41, v42, v43
	v_cvt_pk_bf16_f32 v42, v8, v9
	v_cvt_pk_bf16_f32 v43, v10, v11
	v_or_b32_e32 v152, 0x90, v154
	v_lshlrev_b32_e32 v220, 11, v152
	v_lshl_add_u64 v[150:151], v[142:143], 0, v[220:221]
	global_store_dwordx4 v[150:151], v[40:43], off offset:768
	s_waitcnt vmcnt(10)
	v_pk_fma_f32 v[36:37], v[36:37], s[98:99], v[92:93]
	v_pk_fma_f32 v[38:39], v[38:39], s[98:99], v[94:95]
	v_pk_fma_f32 v[4:5], v[4:5], s[98:99], v[88:89]
	v_pk_fma_f32 v[6:7], v[6:7], s[98:99], v[90:91]
	v_exp_f32_e32 v36, v36
	v_exp_f32_e32 v37, v37
	v_exp_f32_e32 v38, v38
	v_exp_f32_e32 v39, v39
	v_exp_f32_e32 v4, v4
	v_exp_f32_e32 v5, v5
	v_exp_f32_e32 v6, v6
	v_exp_f32_e32 v7, v7
	v_pk_add_f32 v[36:37], v[36:37], v[242:243]
	v_pk_add_f32 v[38:39], v[38:39], v[242:243]
	v_pk_add_f32 v[4:5], v[4:5], v[242:243]
	v_pk_add_f32 v[6:7], v[6:7], v[242:243]
	v_rcp_f32_e32 v36, v36
	v_rcp_f32_e32 v37, v37
	v_rcp_f32_e32 v38, v38
	v_rcp_f32_e32 v39, v39
	v_rcp_f32_e32 v4, v4
	v_rcp_f32_e32 v5, v5
	v_rcp_f32_e32 v6, v6
	v_rcp_f32_e32 v7, v7
	v_lshlrev_b32_e32 v244, 16, v76
	v_and_b32_e32 v245, 0xffff0000, v76
	v_lshlrev_b32_e32 v246, 16, v77
	v_and_b32_e32 v247, 0xffff0000, v77
	v_pk_mul_f32 v[36:37], v[36:37], v[244:245]
	v_pk_mul_f32 v[38:39], v[38:39], v[246:247]
	v_lshlrev_b32_e32 v244, 16, v78
	v_and_b32_e32 v245, 0xffff0000, v78
	v_lshlrev_b32_e32 v246, 16, v79
	v_and_b32_e32 v247, 0xffff0000, v79
	v_pk_mul_f32 v[4:5], v[4:5], v[244:245]
	v_pk_mul_f32 v[6:7], v[6:7], v[246:247]
	v_cvt_pk_bf16_f32 v36, v36, v37
	v_cvt_pk_bf16_f32 v37, v38, v39
	v_cvt_pk_bf16_f32 v38, v4, v5
	v_cvt_pk_bf16_f32 v39, v6, v7
	v_or_b32_e32 v152, 0xa0, v154
	v_lshlrev_b32_e32 v220, 11, v152
	v_lshl_add_u64 v[150:151], v[142:143], 0, v[220:221]
	global_store_dwordx4 v[150:151], v[36:39], off offset:768
	s_waitcnt vmcnt(9)
	v_pk_fma_f32 v[32:33], v[32:33], s[98:99], v[92:93]
	v_pk_fma_f32 v[34:35], v[34:35], s[98:99], v[94:95]
	v_pk_fma_f32 v[0:1], v[0:1], s[98:99], v[88:89]
	v_pk_fma_f32 v[2:3], v[2:3], s[98:99], v[90:91]
	v_exp_f32_e32 v32, v32
	v_exp_f32_e32 v33, v33
	v_exp_f32_e32 v34, v34
	v_exp_f32_e32 v35, v35
	v_exp_f32_e32 v0, v0
	v_exp_f32_e32 v1, v1
	v_exp_f32_e32 v2, v2
	v_exp_f32_e32 v3, v3
	v_pk_add_f32 v[32:33], v[32:33], v[242:243]
	v_pk_add_f32 v[34:35], v[34:35], v[242:243]
	v_pk_add_f32 v[0:1], v[0:1], v[242:243]
	v_pk_add_f32 v[2:3], v[2:3], v[242:243]
	v_rcp_f32_e32 v32, v32
	v_rcp_f32_e32 v33, v33
	v_rcp_f32_e32 v34, v34
	v_rcp_f32_e32 v35, v35
	v_rcp_f32_e32 v0, v0
	v_rcp_f32_e32 v1, v1
	v_rcp_f32_e32 v2, v2
	v_rcp_f32_e32 v3, v3
	v_lshlrev_b32_e32 v244, 16, v72
	v_and_b32_e32 v245, 0xffff0000, v72
	v_lshlrev_b32_e32 v246, 16, v73
	v_and_b32_e32 v247, 0xffff0000, v73
	v_pk_mul_f32 v[32:33], v[32:33], v[244:245]
	v_pk_mul_f32 v[34:35], v[34:35], v[246:247]
	v_lshlrev_b32_e32 v244, 16, v74
	v_and_b32_e32 v245, 0xffff0000, v74
	v_lshlrev_b32_e32 v246, 16, v75
	v_and_b32_e32 v247, 0xffff0000, v75
	v_pk_mul_f32 v[0:1], v[0:1], v[244:245]
	v_pk_mul_f32 v[2:3], v[2:3], v[246:247]
	v_cvt_pk_bf16_f32 v32, v32, v33
	v_cvt_pk_bf16_f32 v33, v34, v35
	v_cvt_pk_bf16_f32 v34, v0, v1
	v_cvt_pk_bf16_f32 v35, v2, v3
	v_or_b32_e32 v152, 0xb0, v154
	v_lshlrev_b32_e32 v220, 11, v152
	v_lshl_add_u64 v[150:151], v[142:143], 0, v[220:221]
	global_store_dwordx4 v[150:151], v[32:35], off offset:768
	s_cbranch_vccnz .LBB0_827
	s_andn2_b64 vcc, exec, s[24:25]
	s_cbranch_vccnz .LBB0_826
	s_barrier
	s_branch .LBB0_826
